# v34 plus: per-XCD release word published by a plain store (stays in the XCD's L2, found there by the same-XCD pollers' sc1 loads) instead of a memory-side atomic add
# speedup vs baseline: 1.0059x; 1.0059x over previous
; __device__ __forceinline__ unsigned xb_ld(unsigned* p)              { return __hip_atomic_load(p, __ATOMIC_RELAXED, __HIP_MEMORY_SCOPE_AGENT); }
; __device__ __forceinline__ unsigned xb_add(unsigned* p, unsigned v) { return __hip_atomic_fetch_add(p, v, __ATOMIC_RELAXED, __HIP_MEMORY_SCOPE_AGENT); }
; #define XB_SPIN(cond, bar) do { unsigned _sp = 0; while (cond) { __builtin_amdgcn_s_sleep(1); \
;     if ((++_sp & 255u) == 0u) { if (xb_ld(&(bar)[XB_TMO])) break; if (_sp > XB_SPIN_CAP) { atomicAdd(&(bar)[XB_TMO], 1u); break; } } } } while (0)
; __device__ __forceinline__ void xcd_barrier(const XcdBarrier& b) {
;     ...
;             const unsigned og = xb_add(&bar[XB_TOP], 1u);
;             const unsigned tg = og / nx;
;             if (og + 1u == (tg + 1u) * nx) xb_add(&bar[XB_TOPGEN], 1u);
;             else XB_SPIN(xb_ld(&bar[XB_TOPGEN]) == tg, bar);
.LBB0_134:
	s_or_b64 exec, exec, s[14:15]
	v_cvt_f32_u32_e32 v3, v0
	s_waitcnt vmcnt(0)
	v_readfirstlane_b32 s12, v2
	s_add_u32 s14, s24, 0x7500
	s_addc_u32 s15, s25, 0
	v_rcp_iflag_f32_e32 v3, v3
	v_add_u32_e32 v1, s12, v1
	v_add_u32_e32 v4, 1, v1
	s_mov_b64 s[16:17], -1
	v_mul_f32_e32 v2, 0x4f7ffffe, v3
	v_cvt_u32_f32_e32 v2, v2
	v_sub_u32_e32 v3, 0, v0
	v_mul_lo_u32 v3, v3, v2
	v_mul_hi_u32 v3, v2, v3
	v_add_u32_e32 v2, v2, v3
	v_mul_hi_u32 v2, v1, v2
	v_mul_lo_u32 v3, v2, v0
	v_sub_u32_e32 v1, v1, v3
	v_add_u32_e32 v5, 1, v2
	v_cmp_ge_u32_e32 vcc, v1, v0
	v_sub_u32_e32 v3, v1, v0
	s_nop 0
	v_cndmask_b32_e32 v2, v2, v5, vcc
	v_cndmask_b32_e32 v1, v1, v3, vcc
	v_add_u32_e32 v3, 1, v2
	v_cmp_ge_u32_e32 vcc, v1, v0
	s_nop 1
	v_cndmask_b32_e32 v2, v2, v3, vcc
	v_mul_lo_u32 v1, v0, v2
	v_add_u32_e32 v0, v1, v0
	v_cmp_ne_u32_e32 vcc, v4, v0
	v_add_u32_e32 v251, 1, v2
	v_mov_b64_e32 v[0:1], s[14:15]
	s_and_saveexec_b64 s[12:13], vcc
	s_cbranch_execz .LBB0_146
	v_mov_b32_e32 v0, 0
	global_load_dword v1, v0, s[14:15] sc1
	s_mov_b64 s[20:21], 0
	s_waitcnt vmcnt(0)
	v_cmp_eq_u32_e32 vcc, v1, v2
	s_and_saveexec_b64 s[18:19], vcc
	s_cbranch_execz .LBB0_145
	s_add_u32 s16, s24, 0x4200
	s_addc_u32 s17, s25, 0
	s_mov_b32 s33, 1
	s_branch .LBB0_138

; __device__ __forceinline__ unsigned xb_add(unsigned* p, unsigned v) { return __hip_atomic_fetch_add(p, v, __ATOMIC_RELAXED, __HIP_MEMORY_SCOPE_AGENT); }
; __device__ __forceinline__ void xcd_barrier(const XcdBarrier& b) {
;     ...
;             __builtin_amdgcn_fence(__ATOMIC_ACQUIRE, "agent");
;             xb_add(&bar[XB_XGEN(b.x)], 1u);
;             asm volatile("s_waitcnt vmcnt(0)" ::: "memory");
.LBB0_148:
	s_or_b64 exec, exec, s[12:13]
	s_mov_b64 s[12:13], exec
	v_mbcnt_lo_u32_b32 v0, s12, 0
	v_mbcnt_hi_u32_b32 v0, s13, v0
	v_cmp_eq_u32_e32 vcc, 0, v0
	s_and_saveexec_b64 s[14:15], vcc
	s_cbranch_execz .LBB0_150
	s_bcnt1_i32_b64 s12, s[12:13]
	v_mov_b32_e32 v0, 0x2000
	v_mov_b32_e32 v1, s12
	global_store_dword v0, v251, s[10:11] offset:1024

; __device__ __forceinline__ unsigned xb_ld(unsigned* p)              { return __hip_atomic_load(p, __ATOMIC_RELAXED, __HIP_MEMORY_SCOPE_AGENT); }
; __device__ __forceinline__ unsigned xb_add(unsigned* p, unsigned v) { return __hip_atomic_fetch_add(p, v, __ATOMIC_RELAXED, __HIP_MEMORY_SCOPE_AGENT); }
; #define XB_SPIN(cond, bar) do { unsigned _sp = 0; while (cond) { __builtin_amdgcn_s_sleep(1); \
;     if ((++_sp & 255u) == 0u) { if (xb_ld(&(bar)[XB_TMO])) break; if (_sp > XB_SPIN_CAP) { atomicAdd(&(bar)[XB_TMO], 1u); break; } } } } while (0)
; __device__ __forceinline__ void xcd_barrier(const XcdBarrier& b) {
;     ...
;             const unsigned og = xb_add(&bar[XB_TOP], 1u);
;             const unsigned tg = og / nx;
;             if (og + 1u == (tg + 1u) * nx) xb_add(&bar[XB_TOPGEN], 1u);
;             else XB_SPIN(xb_ld(&bar[XB_TOPGEN]) == tg, bar);
.LBB0_345:
	s_or_b64 exec, exec, s[12:13]
	v_cvt_f32_u32_e32 v3, v0
	s_waitcnt vmcnt(0)
	v_readfirstlane_b32 s10, v2
	s_add_u32 s12, s24, 0x7500
	s_addc_u32 s13, s25, 0
	v_rcp_iflag_f32_e32 v3, v3
	v_add_u32_e32 v1, s10, v1
	v_add_u32_e32 v4, 1, v1
	s_mov_b64 s[14:15], -1
	v_mul_f32_e32 v2, 0x4f7ffffe, v3
	v_cvt_u32_f32_e32 v2, v2
	v_sub_u32_e32 v3, 0, v0
	v_mul_lo_u32 v3, v3, v2
	v_mul_hi_u32 v3, v2, v3
	v_add_u32_e32 v2, v2, v3
	v_mul_hi_u32 v2, v1, v2
	v_mul_lo_u32 v3, v2, v0
	v_sub_u32_e32 v1, v1, v3
	v_add_u32_e32 v5, 1, v2
	v_cmp_ge_u32_e32 vcc, v1, v0
	v_sub_u32_e32 v3, v1, v0
	s_nop 0
	v_cndmask_b32_e32 v2, v2, v5, vcc
	v_cndmask_b32_e32 v1, v1, v3, vcc
	v_add_u32_e32 v3, 1, v2
	v_cmp_ge_u32_e32 vcc, v1, v0
	s_nop 1
	v_cndmask_b32_e32 v2, v2, v3, vcc
	v_mul_lo_u32 v1, v0, v2
	v_add_u32_e32 v0, v1, v0
	v_cmp_ne_u32_e32 vcc, v4, v0
	v_add_u32_e32 v251, 1, v2
	v_mov_b64_e32 v[0:1], s[12:13]
	s_and_saveexec_b64 s[10:11], vcc
	s_cbranch_execz .LBB0_357
	v_mov_b32_e32 v0, 0
	global_load_dword v1, v0, s[12:13] sc1
	s_mov_b64 s[18:19], 0
	s_waitcnt vmcnt(0)
	v_cmp_eq_u32_e32 vcc, v1, v2
	s_and_saveexec_b64 s[16:17], vcc
	s_cbranch_execz .LBB0_356
	s_add_u32 s14, s24, 0x4200
	s_addc_u32 s15, s25, 0
	s_mov_b32 s30, 1
	s_branch .LBB0_349

; __device__ __forceinline__ unsigned xb_add(unsigned* p, unsigned v) { return __hip_atomic_fetch_add(p, v, __ATOMIC_RELAXED, __HIP_MEMORY_SCOPE_AGENT); }
; __device__ __forceinline__ void xcd_barrier(const XcdBarrier& b) {
;     ...
;             __builtin_amdgcn_fence(__ATOMIC_ACQUIRE, "agent");
;             xb_add(&bar[XB_XGEN(b.x)], 1u);
;             asm volatile("s_waitcnt vmcnt(0)" ::: "memory");
.LBB0_359:
	s_or_b64 exec, exec, s[10:11]
	s_mov_b64 s[10:11], exec
	v_mbcnt_lo_u32_b32 v0, s10, 0
	v_mbcnt_hi_u32_b32 v0, s11, v0
	v_cmp_eq_u32_e32 vcc, 0, v0
	s_and_saveexec_b64 s[12:13], vcc
	s_cbranch_execz .LBB0_361
	s_bcnt1_i32_b64 s10, s[10:11]
	v_mov_b32_e32 v0, 0x2000
	v_mov_b32_e32 v1, s10
	global_store_dword v0, v251, s[8:9] offset:1024

; __device__ __forceinline__ unsigned xb_ld(unsigned* p)              { return __hip_atomic_load(p, __ATOMIC_RELAXED, __HIP_MEMORY_SCOPE_AGENT); }
; __device__ __forceinline__ unsigned xb_add(unsigned* p, unsigned v) { return __hip_atomic_fetch_add(p, v, __ATOMIC_RELAXED, __HIP_MEMORY_SCOPE_AGENT); }
; #define XB_SPIN(cond, bar) do { unsigned _sp = 0; while (cond) { __builtin_amdgcn_s_sleep(1); \
;     if ((++_sp & 255u) == 0u) { if (xb_ld(&(bar)[XB_TMO])) break; if (_sp > XB_SPIN_CAP) { atomicAdd(&(bar)[XB_TMO], 1u); break; } } } } while (0)
; __device__ __forceinline__ void xcd_barrier(const XcdBarrier& b) {
;     ...
;             const unsigned og = xb_add(&bar[XB_TOP], 1u);
;             const unsigned tg = og / nx;
;             if (og + 1u == (tg + 1u) * nx) xb_add(&bar[XB_TOPGEN], 1u);
;             else XB_SPIN(xb_ld(&bar[XB_TOPGEN]) == tg, bar);
.LBB0_436:
	s_or_b64 exec, exec, s[28:29]
	s_waitcnt vmcnt(0)
	v_readfirstlane_b32 s11, v2
	v_cvt_f32_u32_e32 v2, v0
	v_sub_u32_e32 v3, 0, v0
	v_add_u32_e32 v1, s11, v1
	v_readlane_b32 s12, v247, 15
	v_rcp_iflag_f32_e32 v2, v2
	v_readlane_b32 s13, v247, 16
	s_mov_b64 s[28:29], -1
	v_mul_f32_e32 v2, 0x4f7ffffe, v2
	v_cvt_u32_f32_e32 v2, v2
	v_mul_lo_u32 v3, v3, v2
	v_mul_hi_u32 v3, v2, v3
	v_add_u32_e32 v2, v2, v3
	v_mul_hi_u32 v2, v1, v2
	v_mul_lo_u32 v3, v2, v0
	v_sub_u32_e32 v3, v1, v3
	v_cmp_ge_u32_e32 vcc, v3, v0
	v_add_u32_e32 v4, 1, v2
	v_add_u32_e32 v1, 1, v1
	v_cndmask_b32_e32 v2, v2, v4, vcc
	v_sub_u32_e32 v4, v3, v0
	v_cndmask_b32_e32 v3, v3, v4, vcc
	v_cmp_ge_u32_e32 vcc, v3, v0
	v_add_u32_e32 v3, 1, v2
	s_nop 0
	v_cndmask_b32_e32 v2, v2, v3, vcc
	v_mul_lo_u32 v3, v0, v2
	v_add_u32_e32 v0, v3, v0
	v_cmp_ne_u32_e32 vcc, v1, v0
	v_add_u32_e32 v251, 1, v2
	v_mov_b64_e32 v[0:1], s[12:13]
	s_and_saveexec_b64 s[22:23], vcc
	s_cbranch_execz .LBB0_448
	v_readlane_b32 s12, v247, 15
	v_readlane_b32 s13, v247, 16
	s_mov_b64 s[36:37], 0
	s_nop 3
	global_load_dword v0, v173, s[12:13] sc1
	s_waitcnt vmcnt(0)
	v_cmp_eq_u32_e32 vcc, v0, v2
	s_and_saveexec_b64 s[28:29], vcc
	s_cbranch_execz .LBB0_447
	s_mov_b32 s11, 1
	s_branch .LBB0_440

; __device__ __forceinline__ unsigned xb_add(unsigned* p, unsigned v) { return __hip_atomic_fetch_add(p, v, __ATOMIC_RELAXED, __HIP_MEMORY_SCOPE_AGENT); }
; __device__ __forceinline__ void xcd_barrier(const XcdBarrier& b) {
;     ...
;             __builtin_amdgcn_fence(__ATOMIC_ACQUIRE, "agent");
;             xb_add(&bar[XB_XGEN(b.x)], 1u);
;             asm volatile("s_waitcnt vmcnt(0)" ::: "memory");
.LBB0_450:
	s_or_b64 exec, exec, s[22:23]
	s_mov_b64 s[22:23], exec
	v_mbcnt_lo_u32_b32 v0, s22, 0
	v_mbcnt_hi_u32_b32 v0, s23, v0
	v_cmp_eq_u32_e32 vcc, 0, v0
	s_and_saveexec_b64 s[28:29], vcc
	s_cbranch_execz .LBB0_452
	s_bcnt1_i32_b64 s11, s[22:23]
	v_readlane_b32 s12, v247, 11
	v_mov_b32_e32 v0, s11
	v_readlane_b32 s13, v247, 12
	s_nop 4
	global_store_dword v173, v251, s[12:13]

; __device__ __forceinline__ unsigned xb_ld(unsigned* p)              { return __hip_atomic_load(p, __ATOMIC_RELAXED, __HIP_MEMORY_SCOPE_AGENT); }
; __device__ __forceinline__ unsigned xb_add(unsigned* p, unsigned v) { return __hip_atomic_fetch_add(p, v, __ATOMIC_RELAXED, __HIP_MEMORY_SCOPE_AGENT); }
; #define XB_SPIN(cond, bar) do { unsigned _sp = 0; while (cond) { __builtin_amdgcn_s_sleep(1); \
;     if ((++_sp & 255u) == 0u) { if (xb_ld(&(bar)[XB_TMO])) break; if (_sp > XB_SPIN_CAP) { atomicAdd(&(bar)[XB_TMO], 1u); break; } } } } while (0)
; __device__ __forceinline__ void xcd_barrier(const XcdBarrier& b) {
;     ...
;             const unsigned og = xb_add(&bar[XB_TOP], 1u);
;             const unsigned tg = og / nx;
;             if (og + 1u == (tg + 1u) * nx) xb_add(&bar[XB_TOPGEN], 1u);
;             else XB_SPIN(xb_ld(&bar[XB_TOPGEN]) == tg, bar);
.LBB0_1406:
	s_or_b64 exec, exec, s[28:29]
	s_waitcnt vmcnt(0)
	v_readfirstlane_b32 s6, v2
	v_cvt_f32_u32_e32 v2, v0
	v_sub_u32_e32 v3, 0, v0
	v_add_u32_e32 v1, s6, v1
	v_readlane_b32 s16, v247, 15
	v_rcp_iflag_f32_e32 v2, v2
	v_readlane_b32 s17, v247, 16
	s_mov_b64 s[28:29], -1
	v_mul_f32_e32 v2, 0x4f7ffffe, v2
	v_cvt_u32_f32_e32 v2, v2
	v_mul_lo_u32 v3, v3, v2
	v_mul_hi_u32 v3, v2, v3
	v_add_u32_e32 v2, v2, v3
	v_mul_hi_u32 v2, v1, v2
	v_mul_lo_u32 v3, v2, v0
	v_sub_u32_e32 v3, v1, v3
	v_cmp_ge_u32_e32 vcc, v3, v0
	v_add_u32_e32 v4, 1, v2
	v_add_u32_e32 v1, 1, v1
	v_cndmask_b32_e32 v2, v2, v4, vcc
	v_sub_u32_e32 v4, v3, v0
	v_cndmask_b32_e32 v3, v3, v4, vcc
	v_cmp_ge_u32_e32 vcc, v3, v0
	v_add_u32_e32 v3, 1, v2
	s_nop 0
	v_cndmask_b32_e32 v2, v2, v3, vcc
	v_mul_lo_u32 v3, v0, v2
	v_add_u32_e32 v0, v3, v0
	v_cmp_ne_u32_e32 vcc, v1, v0
	v_add_u32_e32 v251, 1, v2
	v_mov_b64_e32 v[0:1], s[16:17]
	s_and_saveexec_b64 s[22:23], vcc
	s_cbranch_execz .LBB0_1418
	v_readlane_b32 s16, v247, 15
	v_readlane_b32 s17, v247, 16
	s_mov_b64 s[36:37], 0
	s_nop 3
	global_load_dword v0, v173, s[16:17] sc1
	s_waitcnt vmcnt(0)
	v_cmp_eq_u32_e32 vcc, v0, v2
	s_and_saveexec_b64 s[28:29], vcc
	s_cbranch_execz .LBB0_1417
	s_mov_b32 s6, 1
	s_branch .LBB0_1410

; __device__ __forceinline__ unsigned xb_add(unsigned* p, unsigned v) { return __hip_atomic_fetch_add(p, v, __ATOMIC_RELAXED, __HIP_MEMORY_SCOPE_AGENT); }
; __device__ __forceinline__ void xcd_barrier(const XcdBarrier& b) {
;     ...
;             __builtin_amdgcn_fence(__ATOMIC_ACQUIRE, "agent");
;             xb_add(&bar[XB_XGEN(b.x)], 1u);
;             asm volatile("s_waitcnt vmcnt(0)" ::: "memory");
.LBB0_1420:
	s_or_b64 exec, exec, s[22:23]
	s_mov_b64 s[22:23], exec
	v_mbcnt_lo_u32_b32 v0, s22, 0
	v_mbcnt_hi_u32_b32 v0, s23, v0
	v_cmp_eq_u32_e32 vcc, 0, v0
	s_and_saveexec_b64 s[28:29], vcc
	s_cbranch_execz .LBB0_1422
	s_bcnt1_i32_b64 s6, s[22:23]
	v_readlane_b32 s16, v247, 11
	v_mov_b32_e32 v0, s6
	v_readlane_b32 s17, v247, 12
	s_nop 4
	global_store_dword v173, v251, s[16:17]

; __device__ __forceinline__ unsigned xb_ld(unsigned* p)              { return __hip_atomic_load(p, __ATOMIC_RELAXED, __HIP_MEMORY_SCOPE_AGENT); }
; __device__ __forceinline__ unsigned xb_add(unsigned* p, unsigned v) { return __hip_atomic_fetch_add(p, v, __ATOMIC_RELAXED, __HIP_MEMORY_SCOPE_AGENT); }
; #define XB_SPIN(cond, bar) do { unsigned _sp = 0; while (cond) { __builtin_amdgcn_s_sleep(1); \
;     if ((++_sp & 255u) == 0u) { if (xb_ld(&(bar)[XB_TMO])) break; if (_sp > XB_SPIN_CAP) { atomicAdd(&(bar)[XB_TMO], 1u); break; } } } } while (0)
; __device__ __forceinline__ void xcd_barrier(const XcdBarrier& b) {
;     ...
;             const unsigned og = xb_add(&bar[XB_TOP], 1u);
;             const unsigned tg = og / nx;
;             if (og + 1u == (tg + 1u) * nx) xb_add(&bar[XB_TOPGEN], 1u);
;             else XB_SPIN(xb_ld(&bar[XB_TOPGEN]) == tg, bar);
.LBB0_1558:
	s_or_b64 exec, exec, s[36:37]
	s_waitcnt vmcnt(0)
	v_readfirstlane_b32 s11, v2
	v_cvt_f32_u32_e32 v2, v0
	v_sub_u32_e32 v3, 0, v0
	v_add_u32_e32 v1, s11, v1
	v_readlane_b32 s12, v247, 15
	v_rcp_iflag_f32_e32 v2, v2
	v_readlane_b32 s13, v247, 16
	s_mov_b64 s[36:37], -1
	v_mul_f32_e32 v2, 0x4f7ffffe, v2
	v_cvt_u32_f32_e32 v2, v2
	v_mul_lo_u32 v3, v3, v2
	v_mul_hi_u32 v3, v2, v3
	v_add_u32_e32 v2, v2, v3
	v_mul_hi_u32 v2, v1, v2
	v_mul_lo_u32 v3, v2, v0
	v_sub_u32_e32 v3, v1, v3
	v_cmp_ge_u32_e32 vcc, v3, v0
	v_add_u32_e32 v4, 1, v2
	v_add_u32_e32 v1, 1, v1
	v_cndmask_b32_e32 v2, v2, v4, vcc
	v_sub_u32_e32 v4, v3, v0
	v_cndmask_b32_e32 v3, v3, v4, vcc
	v_cmp_ge_u32_e32 vcc, v3, v0
	v_add_u32_e32 v3, 1, v2
	s_nop 0
	v_cndmask_b32_e32 v2, v2, v3, vcc
	v_mul_lo_u32 v3, v0, v2
	v_add_u32_e32 v0, v3, v0
	v_cmp_ne_u32_e32 vcc, v1, v0
	v_add_u32_e32 v251, 1, v2
	v_mov_b64_e32 v[0:1], s[12:13]
	s_and_saveexec_b64 s[22:23], vcc
	s_cbranch_execz .LBB0_1570
	v_readlane_b32 s12, v247, 15
	v_readlane_b32 s13, v247, 16
	s_mov_b64 s[40:41], 0
	s_nop 3
	global_load_dword v0, v173, s[12:13] sc1
	s_waitcnt vmcnt(0)
	v_cmp_eq_u32_e32 vcc, v0, v2
	s_and_saveexec_b64 s[36:37], vcc
	s_cbranch_execz .LBB0_1569
	s_mov_b32 s11, 1
	s_branch .LBB0_1562

; __device__ __forceinline__ unsigned xb_ld(unsigned* p)              { return __hip_atomic_load(p, __ATOMIC_RELAXED, __HIP_MEMORY_SCOPE_AGENT); }
; __device__ __forceinline__ unsigned xb_add(unsigned* p, unsigned v) { return __hip_atomic_fetch_add(p, v, __ATOMIC_RELAXED, __HIP_MEMORY_SCOPE_AGENT); }
; #define XB_SPIN(cond, bar) do { unsigned _sp = 0; while (cond) { __builtin_amdgcn_s_sleep(1); \
;     if ((++_sp & 255u) == 0u) { if (xb_ld(&(bar)[XB_TMO])) break; if (_sp > XB_SPIN_CAP) { atomicAdd(&(bar)[XB_TMO], 1u); break; } } } } while (0)
; __device__ __forceinline__ void xcd_barrier(const XcdBarrier& b) {
;     ...
;             const unsigned og = xb_add(&bar[XB_TOP], 1u);
;             const unsigned tg = og / nx;
;             if (og + 1u == (tg + 1u) * nx) xb_add(&bar[XB_TOPGEN], 1u);
;             else XB_SPIN(xb_ld(&bar[XB_TOPGEN]) == tg, bar);
.LBB0_1668:
	s_or_b64 exec, exec, s[28:29]
	s_waitcnt vmcnt(0)
	v_readfirstlane_b32 s11, v2
	v_cvt_f32_u32_e32 v2, v0
	v_sub_u32_e32 v3, 0, v0
	v_add_u32_e32 v1, s11, v1
	v_readlane_b32 s12, v247, 15
	v_rcp_iflag_f32_e32 v2, v2
	v_readlane_b32 s13, v247, 16
	s_mov_b64 s[36:37], -1
	v_mul_f32_e32 v2, 0x4f7ffffe, v2
	v_cvt_u32_f32_e32 v2, v2
	v_mul_lo_u32 v3, v3, v2
	v_mul_hi_u32 v3, v2, v3
	v_add_u32_e32 v2, v2, v3
	v_mul_hi_u32 v2, v1, v2
	v_mul_lo_u32 v3, v2, v0
	v_sub_u32_e32 v3, v1, v3
	v_cmp_ge_u32_e32 vcc, v3, v0
	v_add_u32_e32 v4, 1, v2
	v_add_u32_e32 v1, 1, v1
	v_cndmask_b32_e32 v2, v2, v4, vcc
	v_sub_u32_e32 v4, v3, v0
	v_cndmask_b32_e32 v3, v3, v4, vcc
	v_cmp_ge_u32_e32 vcc, v3, v0
	v_add_u32_e32 v3, 1, v2
	s_nop 0
	v_cndmask_b32_e32 v2, v2, v3, vcc
	v_mul_lo_u32 v3, v0, v2
	v_add_u32_e32 v0, v3, v0
	v_cmp_ne_u32_e32 vcc, v1, v0
	v_add_u32_e32 v251, 1, v2
	v_mov_b64_e32 v[0:1], s[12:13]
	s_and_saveexec_b64 s[22:23], vcc
	s_cbranch_execz .LBB0_1680
	v_readlane_b32 s12, v247, 15
	v_readlane_b32 s13, v247, 16
	s_mov_b64 s[40:41], 0
	s_nop 3
	global_load_dword v0, v173, s[12:13] sc1
	s_waitcnt vmcnt(0)
	v_cmp_eq_u32_e32 vcc, v0, v2
	s_and_saveexec_b64 s[36:37], vcc
	s_cbranch_execz .LBB0_1679
	s_mov_b32 s11, 1
	s_branch .LBB0_1672

; __device__ __forceinline__ unsigned xb_ld(unsigned* p)              { return __hip_atomic_load(p, __ATOMIC_RELAXED, __HIP_MEMORY_SCOPE_AGENT); }
; __device__ __forceinline__ unsigned xb_add(unsigned* p, unsigned v) { return __hip_atomic_fetch_add(p, v, __ATOMIC_RELAXED, __HIP_MEMORY_SCOPE_AGENT); }
; #define XB_SPIN(cond, bar) do { unsigned _sp = 0; while (cond) { __builtin_amdgcn_s_sleep(1); \
;     if ((++_sp & 255u) == 0u) { if (xb_ld(&(bar)[XB_TMO])) break; if (_sp > XB_SPIN_CAP) { atomicAdd(&(bar)[XB_TMO], 1u); break; } } } } while (0)
; __device__ __forceinline__ void xcd_barrier(const XcdBarrier& b) {
;     ...
;             const unsigned og = xb_add(&bar[XB_TOP], 1u);
;             const unsigned tg = og / nx;
;             if (og + 1u == (tg + 1u) * nx) xb_add(&bar[XB_TOPGEN], 1u);
;             else XB_SPIN(xb_ld(&bar[XB_TOPGEN]) == tg, bar);
.LBB0_2179:
	s_or_b64 exec, exec, s[26:27]
	s_waitcnt vmcnt(0)
	v_readfirstlane_b32 s6, v2
	v_cvt_f32_u32_e32 v2, v0
	v_sub_u32_e32 v3, 0, v0
	v_add_u32_e32 v1, s6, v1
	v_readlane_b32 s14, v247, 15
	v_rcp_iflag_f32_e32 v2, v2
	v_readlane_b32 s15, v247, 16
	s_mov_b64 s[26:27], -1
	v_mul_f32_e32 v2, 0x4f7ffffe, v2
	v_cvt_u32_f32_e32 v2, v2
	v_mul_lo_u32 v3, v3, v2
	v_mul_hi_u32 v3, v2, v3
	v_add_u32_e32 v2, v2, v3
	v_mul_hi_u32 v2, v1, v2
	v_mul_lo_u32 v3, v2, v0
	v_sub_u32_e32 v3, v1, v3
	v_cmp_ge_u32_e32 vcc, v3, v0
	v_add_u32_e32 v4, 1, v2
	v_add_u32_e32 v1, 1, v1
	v_cndmask_b32_e32 v2, v2, v4, vcc
	v_sub_u32_e32 v4, v3, v0
	v_cndmask_b32_e32 v3, v3, v4, vcc
	v_cmp_ge_u32_e32 vcc, v3, v0
	v_add_u32_e32 v3, 1, v2
	s_nop 0
	v_cndmask_b32_e32 v2, v2, v3, vcc
	v_mul_lo_u32 v3, v0, v2
	v_add_u32_e32 v0, v3, v0
	v_cmp_ne_u32_e32 vcc, v1, v0
	v_add_u32_e32 v251, 1, v2
	v_mov_b64_e32 v[0:1], s[14:15]
	s_and_saveexec_b64 s[22:23], vcc
	s_cbranch_execz .LBB0_2191
	v_readlane_b32 s14, v247, 15
	v_readlane_b32 s15, v247, 16
	s_mov_b64 s[28:29], 0
	s_nop 3
	global_load_dword v0, v173, s[14:15] sc1
	s_waitcnt vmcnt(0)
	v_cmp_eq_u32_e32 vcc, v0, v2
	s_and_saveexec_b64 s[26:27], vcc
	s_cbranch_execz .LBB0_2190
	s_mov_b32 s6, 1
	s_branch .LBB0_2183

; __device__ __forceinline__ unsigned xb_add(unsigned* p, unsigned v) { return __hip_atomic_fetch_add(p, v, __ATOMIC_RELAXED, __HIP_MEMORY_SCOPE_AGENT); }
; __device__ __forceinline__ void xcd_barrier(const XcdBarrier& b) {
;     ...
;             __builtin_amdgcn_fence(__ATOMIC_ACQUIRE, "agent");
;             xb_add(&bar[XB_XGEN(b.x)], 1u);
;             asm volatile("s_waitcnt vmcnt(0)" ::: "memory");
.LBB0_2193:
	s_or_b64 exec, exec, s[22:23]
	s_mov_b64 s[22:23], exec
	v_mbcnt_lo_u32_b32 v0, s22, 0
	v_mbcnt_hi_u32_b32 v0, s23, v0
	v_cmp_eq_u32_e32 vcc, 0, v0
	s_and_saveexec_b64 s[26:27], vcc
	s_cbranch_execz .LBB0_2195
	s_bcnt1_i32_b64 s6, s[22:23]
	v_readlane_b32 s14, v247, 11
	v_mov_b32_e32 v0, s6
	v_readlane_b32 s15, v247, 12
	s_nop 4
	global_store_dword v173, v251, s[14:15]

; __device__ __forceinline__ unsigned xb_ld(unsigned* p)              { return __hip_atomic_load(p, __ATOMIC_RELAXED, __HIP_MEMORY_SCOPE_AGENT); }
; __device__ __forceinline__ unsigned xb_add(unsigned* p, unsigned v) { return __hip_atomic_fetch_add(p, v, __ATOMIC_RELAXED, __HIP_MEMORY_SCOPE_AGENT); }
; #define XB_SPIN(cond, bar) do { unsigned _sp = 0; while (cond) { __builtin_amdgcn_s_sleep(1); \
;     if ((++_sp & 255u) == 0u) { if (xb_ld(&(bar)[XB_TMO])) break; if (_sp > XB_SPIN_CAP) { atomicAdd(&(bar)[XB_TMO], 1u); break; } } } } while (0)
; __device__ __forceinline__ void xcd_barrier(const XcdBarrier& b) {
;     ...
;             const unsigned og = xb_add(&bar[XB_TOP], 1u);
;             const unsigned tg = og / nx;
;             if (og + 1u == (tg + 1u) * nx) xb_add(&bar[XB_TOPGEN], 1u);
;             else XB_SPIN(xb_ld(&bar[XB_TOPGEN]) == tg, bar);
.LBB0_2275:
	s_or_b64 exec, exec, s[36:37]
	s_waitcnt vmcnt(0)
	v_readfirstlane_b32 s11, v2
	v_cvt_f32_u32_e32 v2, v0
	v_sub_u32_e32 v3, 0, v0
	v_add_u32_e32 v1, s11, v1
	v_readlane_b32 s14, v247, 15
	v_rcp_iflag_f32_e32 v2, v2
	v_readlane_b32 s15, v247, 16
	s_mov_b64 s[36:37], -1
	v_mul_f32_e32 v2, 0x4f7ffffe, v2
	v_cvt_u32_f32_e32 v2, v2
	v_mul_lo_u32 v3, v3, v2
	v_mul_hi_u32 v3, v2, v3
	v_add_u32_e32 v2, v2, v3
	v_mul_hi_u32 v2, v1, v2
	v_mul_lo_u32 v3, v2, v0
	v_sub_u32_e32 v3, v1, v3
	v_cmp_ge_u32_e32 vcc, v3, v0
	v_add_u32_e32 v4, 1, v2
	v_add_u32_e32 v1, 1, v1
	v_cndmask_b32_e32 v2, v2, v4, vcc
	v_sub_u32_e32 v4, v3, v0
	v_cndmask_b32_e32 v3, v3, v4, vcc
	v_cmp_ge_u32_e32 vcc, v3, v0
	v_add_u32_e32 v3, 1, v2
	s_nop 0
	v_cndmask_b32_e32 v2, v2, v3, vcc
	v_mul_lo_u32 v3, v0, v2
	v_add_u32_e32 v0, v3, v0
	v_cmp_ne_u32_e32 vcc, v1, v0
	v_add_u32_e32 v251, 1, v2
	v_mov_b64_e32 v[0:1], s[14:15]
	s_and_saveexec_b64 s[22:23], vcc
	s_cbranch_execz .LBB0_2287
	v_readlane_b32 s14, v247, 15
	v_readlane_b32 s15, v247, 16
	s_mov_b64 s[40:41], 0
	s_nop 3
	global_load_dword v0, v173, s[14:15] sc1
	s_waitcnt vmcnt(0)
	v_cmp_eq_u32_e32 vcc, v0, v2
	s_and_saveexec_b64 s[36:37], vcc
	s_cbranch_execz .LBB0_2286
	s_mov_b32 s11, 1
	s_branch .LBB0_2279

; __device__ __forceinline__ unsigned xb_add(unsigned* p, unsigned v) { return __hip_atomic_fetch_add(p, v, __ATOMIC_RELAXED, __HIP_MEMORY_SCOPE_AGENT); }
; __device__ __forceinline__ void xcd_barrier(const XcdBarrier& b) {
;     ...
;             __builtin_amdgcn_fence(__ATOMIC_ACQUIRE, "agent");
;             xb_add(&bar[XB_XGEN(b.x)], 1u);
;             asm volatile("s_waitcnt vmcnt(0)" ::: "memory");
.LBB0_2289:
	s_or_b64 exec, exec, s[22:23]
	s_mov_b64 s[22:23], exec
	v_mbcnt_lo_u32_b32 v0, s22, 0
	v_mbcnt_hi_u32_b32 v0, s23, v0
	v_cmp_eq_u32_e32 vcc, 0, v0
	s_and_saveexec_b64 s[36:37], vcc
	s_cbranch_execz .LBB0_2291
	s_bcnt1_i32_b64 s11, s[22:23]
	v_readlane_b32 s14, v247, 11
	v_mov_b32_e32 v0, s11
	v_readlane_b32 s15, v247, 12
	s_nop 4
	global_store_dword v173, v251, s[14:15]

; __device__ __forceinline__ unsigned xb_ld(unsigned* p)              { return __hip_atomic_load(p, __ATOMIC_RELAXED, __HIP_MEMORY_SCOPE_AGENT); }
; __device__ __forceinline__ unsigned xb_add(unsigned* p, unsigned v) { return __hip_atomic_fetch_add(p, v, __ATOMIC_RELAXED, __HIP_MEMORY_SCOPE_AGENT); }
; #define XB_SPIN(cond, bar) do { unsigned _sp = 0; while (cond) { __builtin_amdgcn_s_sleep(1); \
;     if ((++_sp & 255u) == 0u) { if (xb_ld(&(bar)[XB_TMO])) break; if (_sp > XB_SPIN_CAP) { atomicAdd(&(bar)[XB_TMO], 1u); break; } } } } while (0)
; __device__ __forceinline__ void xcd_barrier(const XcdBarrier& b) {
;     ...
;             const unsigned og = xb_add(&bar[XB_TOP], 1u);
;             const unsigned tg = og / nx;
;             if (og + 1u == (tg + 1u) * nx) xb_add(&bar[XB_TOPGEN], 1u);
;             else XB_SPIN(xb_ld(&bar[XB_TOPGEN]) == tg, bar);
.LBB0_2567:
	s_or_b64 exec, exec, s[30:31]
	s_waitcnt vmcnt(0)
	v_readfirstlane_b32 s6, v2
	v_cvt_f32_u32_e32 v2, v0
	v_sub_u32_e32 v3, 0, v0
	v_add_u32_e32 v1, s6, v1
	v_readlane_b32 s16, v247, 15
	v_rcp_iflag_f32_e32 v2, v2
	v_readlane_b32 s17, v247, 16
	s_mov_b64 s[30:31], -1
	v_mul_f32_e32 v2, 0x4f7ffffe, v2
	v_cvt_u32_f32_e32 v2, v2
	v_mul_lo_u32 v3, v3, v2
	v_mul_hi_u32 v3, v2, v3
	v_add_u32_e32 v2, v2, v3
	v_mul_hi_u32 v2, v1, v2
	v_mul_lo_u32 v3, v2, v0
	v_sub_u32_e32 v3, v1, v3
	v_cmp_ge_u32_e32 vcc, v3, v0
	v_add_u32_e32 v4, 1, v2
	v_add_u32_e32 v1, 1, v1
	v_cndmask_b32_e32 v2, v2, v4, vcc
	v_sub_u32_e32 v4, v3, v0
	v_cndmask_b32_e32 v3, v3, v4, vcc
	v_cmp_ge_u32_e32 vcc, v3, v0
	v_add_u32_e32 v3, 1, v2
	s_nop 0
	v_cndmask_b32_e32 v2, v2, v3, vcc
	v_mul_lo_u32 v3, v0, v2
	v_add_u32_e32 v0, v3, v0
	v_cmp_ne_u32_e32 vcc, v1, v0
	v_add_u32_e32 v251, 1, v2
	v_mov_b64_e32 v[0:1], s[16:17]
	s_and_saveexec_b64 s[22:23], vcc
	s_cbranch_execz .LBB0_2579
	v_readlane_b32 s16, v247, 15
	v_readlane_b32 s17, v247, 16
	s_mov_b64 s[36:37], 0
	s_nop 3
	global_load_dword v0, v173, s[16:17] sc1
	s_waitcnt vmcnt(0)
	v_cmp_eq_u32_e32 vcc, v0, v2
	s_and_saveexec_b64 s[30:31], vcc
	s_cbranch_execz .LBB0_2578
	s_mov_b32 s6, 1
	s_branch .LBB0_2571

; __device__ __forceinline__ unsigned xb_add(unsigned* p, unsigned v) { return __hip_atomic_fetch_add(p, v, __ATOMIC_RELAXED, __HIP_MEMORY_SCOPE_AGENT); }
; __device__ __forceinline__ void xcd_barrier(const XcdBarrier& b) {
;     ...
;             __builtin_amdgcn_fence(__ATOMIC_ACQUIRE, "agent");
;             xb_add(&bar[XB_XGEN(b.x)], 1u);
;             asm volatile("s_waitcnt vmcnt(0)" ::: "memory");
.LBB0_2582:
	s_bcnt1_i32_b64 s6, s[22:23]
	v_readlane_b32 s16, v247, 11
	v_mov_b32_e32 v0, s6
	v_readlane_b32 s17, v247, 12
	s_nop 4
	global_store_dword v173, v251, s[16:17]
	s_getpc_b64 s[98:99]

; __device__ __forceinline__ unsigned xb_ld(unsigned* p)              { return __hip_atomic_load(p, __ATOMIC_RELAXED, __HIP_MEMORY_SCOPE_AGENT); }
; __device__ __forceinline__ unsigned xb_add(unsigned* p, unsigned v) { return __hip_atomic_fetch_add(p, v, __ATOMIC_RELAXED, __HIP_MEMORY_SCOPE_AGENT); }
; #define XB_SPIN(cond, bar) do { unsigned _sp = 0; while (cond) { __builtin_amdgcn_s_sleep(1); \
;     if ((++_sp & 255u) == 0u) { if (xb_ld(&(bar)[XB_TMO])) break; if (_sp > XB_SPIN_CAP) { atomicAdd(&(bar)[XB_TMO], 1u); break; } } } } while (0)
; __device__ __forceinline__ void xcd_barrier(const XcdBarrier& b) {
;     ...
;             const unsigned og = xb_add(&bar[XB_TOP], 1u);
;             const unsigned tg = og / nx;
;             if (og + 1u == (tg + 1u) * nx) xb_add(&bar[XB_TOPGEN], 1u);
;             else XB_SPIN(xb_ld(&bar[XB_TOPGEN]) == tg, bar);
.LBB0_2635:
	s_or_b64 exec, exec, s[4:5]
	v_cvt_f32_u32_e32 v3, v0
	s_waitcnt vmcnt(0)
	v_readfirstlane_b32 s2, v2
	s_mov_b64 s[4:5], -1
	v_rcp_iflag_f32_e32 v3, v3
	v_add_u32_e32 v1, s2, v1
	v_add_u32_e32 v4, 1, v1
	v_mul_f32_e32 v2, 0x4f7ffffe, v3
	v_cvt_u32_f32_e32 v2, v2
	v_sub_u32_e32 v3, 0, v0
	v_mul_lo_u32 v3, v3, v2
	v_mul_hi_u32 v3, v2, v3
	v_add_u32_e32 v2, v2, v3
	v_mul_hi_u32 v2, v1, v2
	v_mul_lo_u32 v3, v2, v0
	v_sub_u32_e32 v1, v1, v3
	v_add_u32_e32 v5, 1, v2
	v_cmp_ge_u32_e32 vcc, v1, v0
	v_sub_u32_e32 v3, v1, v0
	s_nop 0
	v_cndmask_b32_e32 v2, v2, v5, vcc
	v_cndmask_b32_e32 v1, v1, v3, vcc
	v_add_u32_e32 v3, 1, v2
	v_cmp_ge_u32_e32 vcc, v1, v0
	s_nop 1
	v_cndmask_b32_e32 v2, v2, v3, vcc
	v_mul_lo_u32 v1, v0, v2
	v_add_u32_e32 v0, v1, v0
	v_cmp_ne_u32_e32 vcc, v4, v0
	v_add_u32_e32 v251, 1, v2
	v_mov_b64_e32 v[0:1], s[18:19]
	s_and_saveexec_b64 s[2:3], vcc
	s_cbranch_execz .LBB0_2647
	v_mov_b32_e32 v0, 0
	global_load_dword v1, v0, s[18:19] sc1
	s_mov_b64 s[6:7], 0
	s_waitcnt vmcnt(0)
	v_cmp_eq_u32_e32 vcc, v1, v2
	s_and_saveexec_b64 s[4:5], vcc
	s_cbranch_execz .LBB0_2646
	s_mov_b32 s16, 1
	s_branch .LBB0_2639

; __device__ __forceinline__ unsigned xb_add(unsigned* p, unsigned v) { return __hip_atomic_fetch_add(p, v, __ATOMIC_RELAXED, __HIP_MEMORY_SCOPE_AGENT); }
; __device__ __forceinline__ void xcd_barrier(const XcdBarrier& b) {
;     ...
;             __builtin_amdgcn_fence(__ATOMIC_ACQUIRE, "agent");
;             xb_add(&bar[XB_XGEN(b.x)], 1u);
;             asm volatile("s_waitcnt vmcnt(0)" ::: "memory");
.LBB0_2649:
	s_or_b64 exec, exec, s[2:3]
	s_mov_b64 s[2:3], exec
	v_mbcnt_lo_u32_b32 v0, s2, 0
	v_mbcnt_hi_u32_b32 v0, s3, v0
	v_cmp_eq_u32_e32 vcc, 0, v0
	s_and_saveexec_b64 s[4:5], vcc
	s_cbranch_execz .LBB0_2651
	s_bcnt1_i32_b64 s2, s[2:3]
	v_mov_b32_e32 v1, s2
	v_readlane_b32 s2, v247, 11
	v_mov_b32_e32 v0, 0
	v_readlane_b32 s3, v247, 12
	s_nop 4
	global_store_dword v0, v251, s[2:3]
